# conv: four (c,z) row-pair loads in flight (4 landing zones) instead of ten serialized round trips (stacked)
# speedup vs baseline: 1.0069x; 1.0069x over previous
.LBB0_227:
	s_lshl_b32 s0, s2, 4
	v_or_b32_e32 v86, s0, v102
	v_mad_i64_i32 v[24:25], s[18:19], v86, s6, v[56:57]
	v_add_co_u32_e32 v26, vcc, 0x1000, v24
	global_load_dwordx4 v[52:55], v[24:25], off
	global_load_dwordx4 v[48:51], v[24:25], off offset:3584
	v_addc_co_u32_e32 v27, vcc, 0, v25, vcc
	global_load_dwordx4 v[44:47], v[26:27], off offset:3072
	v_add_co_u32_e32 v26, vcc, s15, v24
	s_bfe_i32 s0, s2, 0x1001b
	s_nop 0
	v_addc_co_u32_e32 v27, vcc, 0, v25, vcc
	global_load_dwordx4 v[40:43], v[26:27], off offset:2560
	v_add_co_u32_e32 v26, vcc, s35, v24
	v_ashrrev_i32_e32 v87, 31, v86
	s_nop 0
	v_addc_co_u32_e32 v27, vcc, 0, v25, vcc
	global_load_dwordx4 v[36:39], v[26:27], off offset:2048
	v_add_co_u32_e32 v26, vcc, s44, v24
	s_lshr_b32 s0, s0, 19
	s_nop 0
	v_addc_co_u32_e32 v27, vcc, 0, v25, vcc
	v_lshlrev_b64 v[84:85], 11, v[86:87]
	global_load_dwordx4 v[32:35], v[26:27], off offset:1536
	v_add_co_u32_e32 v26, vcc, s46, v24
	v_add_u32_e32 v87, s0, v86
	s_nop 0
	v_addc_co_u32_e32 v27, vcc, 0, v25, vcc
	v_and_b32_e32 v87, 0xffffe000, v87
	v_add_co_u32_e32 v24, vcc, s45, v24
	v_sub_u32_e32 v87, v86, v87
	s_nop 0
	v_addc_co_u32_e32 v25, vcc, 0, v25, vcc
	v_add_u32_e32 v217, -1, v87
	v_cmp_gt_u32_e32 vcc, s15, v217
	global_load_dwordx4 v[28:31], v[26:27], off offset:1024
	v_lshl_add_u64 v[84:85], v[58:59], 0, v[84:85]
	global_load_dwordx4 v[24:27], v[24:25], off offset:512
	s_nop 0
	v_add_u32_e32 v88, -1, v86
	v_max_i32_e32 v88, 0, v88
	v_min_u32_e32 v88, 0xffff, v88
	v_mul_u32_u24_e32 v208, 0xe00, v88
	v_lshl_add_u64 v[92:93], v[56:57], 0, v[208:209]
	global_load_dwordx4 v[88:91], v[92:93], off offset:512
	s_nop 0
	global_load_dwordx4 v[92:95], v[92:93], off offset:1024
	v_add_u32_e32 v218, 0, v86
	v_max_i32_e32 v218, 0, v218
	v_min_u32_e32 v218, 0xffff, v218
	v_mul_u32_u24_e32 v208, 0xe00, v218
	v_lshl_add_u64 v[222:223], v[56:57], 0, v[208:209]
	global_load_dwordx4 v[218:221], v[222:223], off offset:512
	s_nop 0
	global_load_dwordx4 v[222:225], v[222:223], off offset:1024
	v_add_u32_e32 v226, 1, v86
	v_max_i32_e32 v226, 0, v226
	v_min_u32_e32 v226, 0xffff, v226
	v_mul_u32_u24_e32 v208, 0xe00, v226
	v_lshl_add_u64 v[230:231], v[56:57], 0, v[208:209]
	global_load_dwordx4 v[226:229], v[230:231], off offset:512
	s_nop 0
	global_load_dwordx4 v[230:233], v[230:231], off offset:1024
	v_add_u32_e32 v234, 2, v86
	v_max_i32_e32 v234, 0, v234
	v_min_u32_e32 v234, 0xffff, v234
	v_mul_u32_u24_e32 v208, 0xe00, v234
	v_lshl_add_u64 v[238:239], v[56:57], 0, v[208:209]
	global_load_dwordx4 v[234:237], v[238:239], off offset:512
	s_nop 0
	global_load_dwordx4 v[238:241], v[238:239], off offset:1024
	s_add_i32 s2, s2, s3
	s_cmpk_lt_i32 s2, 0x1000
	s_waitcnt vmcnt(6)
	v_cndmask_b32_e32 v97, 0, v88, vcc
	v_cndmask_b32_e32 v149, 0, v93, vcc
	v_cndmask_b32_e32 v98, 0, v92, vcc
	v_cndmask_b32_e32 v141, 0, v91, vcc
	v_cndmask_b32_e32 v143, 0, v90, vcc
	v_cndmask_b32_e32 v96, 0, v89, vcc
	v_cndmask_b32_e32 v145, 0, v95, vcc
	v_cndmask_b32_e32 v147, 0, v94, vcc
	v_add_u32_e32 v88, 3, v86
	v_max_i32_e32 v88, 0, v88
	v_min_u32_e32 v88, 0xffff, v88
	v_mul_u32_u24_e32 v208, 0xe00, v88
	v_lshl_add_u64 v[92:93], v[56:57], 0, v[208:209]
	global_load_dwordx4 v[88:91], v[92:93], off offset:512
	s_nop 0
	global_load_dwordx4 v[92:95], v[92:93], off offset:1024
	v_cmp_lt_i32_e32 vcc, -1, v87
	v_add_u32_e32 v87, 8, v87
	v_and_b32_e32 v186, 0xffff0000, v145
	s_waitcnt vmcnt(6)
	v_cndmask_b32_e32 v146, 0, v218, vcc
	v_cndmask_b32_e32 v152, 0, v223, vcc
	v_cndmask_b32_e32 v144, 0, v222, vcc
	v_cndmask_b32_e32 v99, 0, v221, vcc
	v_cndmask_b32_e32 v100, 0, v220, vcc
	v_cndmask_b32_e32 v101, 0, v219, vcc
	v_cndmask_b32_e32 v151, 0, v225, vcc
	v_cndmask_b32_e32 v153, 0, v224, vcc
	v_add_u32_e32 v218, 4, v86
	v_max_i32_e32 v218, 0, v218
	v_min_u32_e32 v218, 0xffff, v218
	v_mul_u32_u24_e32 v208, 0xe00, v218
	v_lshl_add_u64 v[222:223], v[56:57], 0, v[208:209]
	global_load_dwordx4 v[218:221], v[222:223], off offset:512
	s_nop 0
	global_load_dwordx4 v[222:225], v[222:223], off offset:1024
	v_lshlrev_b32_e32 v150, 16, v101
	v_and_b32_e32 v154, 0xffff0000, v101
	v_lshlrev_b32_e32 v158, 16, v100
	v_and_b32_e32 v162, 0xffff0000, v100
	v_lshlrev_b32_e32 v166, 16, v99
	v_and_b32_e32 v170, 0xffff0000, v99
	v_lshlrev_b32_e32 v140, 16, v144
	v_lshlrev_b32_e32 v142, 16, v146
	v_and_b32_e32 v144, 0xffff0000, v144
	v_and_b32_e32 v146, 0xffff0000, v146
	v_lshlrev_b32_e32 v148, 16, v152
	v_and_b32_e32 v152, 0xffff0000, v152
	v_lshlrev_b32_e32 v156, 16, v153
	v_and_b32_e32 v160, 0xffff0000, v153
	v_lshlrev_b32_e32 v164, 16, v151
	v_and_b32_e32 v168, 0xffff0000, v151
	s_waitcnt vmcnt(6)
	v_cndmask_b32_e32 v161, 0, v226, vcc
	v_cndmask_b32_e32 v167, 0, v231, vcc
	v_cndmask_b32_e32 v169, 0, v230, vcc
	v_cndmask_b32_e32 v155, 0, v229, vcc
	v_cndmask_b32_e32 v157, 0, v228, vcc
	v_cndmask_b32_e32 v159, 0, v227, vcc
	v_cndmask_b32_e32 v163, 0, v233, vcc
	v_cndmask_b32_e32 v165, 0, v232, vcc
	v_add_u32_e32 v226, 5, v86
	v_max_i32_e32 v226, 0, v226
	v_min_u32_e32 v226, 0xffff, v226
	v_mul_u32_u24_e32 v208, 0xe00, v226
	v_lshl_add_u64 v[230:231], v[56:57], 0, v[208:209]
	global_load_dwordx4 v[226:229], v[230:231], off offset:512
	s_nop 0
	global_load_dwordx4 v[230:233], v[230:231], off offset:1024
	v_and_b32_e32 v187, 0xffff0000, v163
	s_waitcnt vmcnt(6)
	v_cndmask_b32_e32 v190, 0, v234, vcc
	v_cndmask_b32_e32 v193, 0, v239, vcc
	v_cndmask_b32_e32 v194, 0, v238, vcc
	v_cndmask_b32_e32 v171, 0, v237, vcc
	v_cndmask_b32_e32 v188, 0, v236, vcc
	v_cndmask_b32_e32 v189, 0, v235, vcc
	v_cndmask_b32_e32 v191, 0, v241, vcc
	v_cndmask_b32_e32 v192, 0, v240, vcc
	v_add_u32_e32 v234, 6, v86
	v_max_i32_e32 v234, 0, v234
	v_min_u32_e32 v234, 0xffff, v234
	v_mul_u32_u24_e32 v208, 0xe00, v234
	v_lshl_add_u64 v[238:239], v[56:57], 0, v[208:209]
	global_load_dwordx4 v[234:237], v[238:239], off offset:512
	s_nop 0
	global_load_dwordx4 v[238:241], v[238:239], off offset:1024
	v_lshlrev_b32_e32 v151, 16, v189
	v_and_b32_e32 v153, 0xffff0000, v193
	s_waitcnt vmcnt(6)
	v_cndmask_b32_e32 v198, 0, v88, vcc
	v_cndmask_b32_e32 v201, 0, v93, vcc
	v_cndmask_b32_e32 v202, 0, v92, vcc
	v_cndmask_b32_e32 v195, 0, v91, vcc
	v_cndmask_b32_e32 v196, 0, v90, vcc
	v_cndmask_b32_e32 v197, 0, v89, vcc
	v_cndmask_b32_e32 v199, 0, v95, vcc
	v_cndmask_b32_e32 v200, 0, v94, vcc
	v_add_u32_e32 v88, 7, v86
	v_max_i32_e32 v88, 0, v88
	v_min_u32_e32 v88, 0xffff, v88
	v_mul_u32_u24_e32 v208, 0xe00, v88
	v_lshl_add_u64 v[92:93], v[56:57], 0, v[208:209]
	global_load_dwordx4 v[88:91], v[92:93], off offset:512
	s_nop 0
	global_load_dwordx4 v[92:95], v[92:93], off offset:1024
	s_waitcnt vmcnt(6)
	v_cndmask_b32_e32 v206, 0, v218, vcc
	v_cndmask_b32_e32 v215, 0, v223, vcc
	v_cndmask_b32_e32 v216, 0, v222, vcc
	v_cndmask_b32_e32 v203, 0, v221, vcc
	v_cndmask_b32_e32 v204, 0, v220, vcc
	v_cndmask_b32_e32 v205, 0, v219, vcc
	v_cndmask_b32_e32 v207, 0, v225, vcc
	v_cndmask_b32_e32 v214, 0, v224, vcc
	v_add_u32_e32 v218, 8, v86
	v_max_i32_e32 v218, 0, v218
	v_min_u32_e32 v218, 0xffff, v218
	v_mul_u32_u24_e32 v208, 0xe00, v218
	v_lshl_add_u64 v[222:223], v[56:57], 0, v[208:209]
	global_load_dwordx4 v[218:221], v[222:223], off offset:512
	s_nop 0
	global_load_dwordx4 v[222:225], v[222:223], off offset:1024
	s_waitcnt vmcnt(6)
	v_cndmask_b32_e32 v136, 0, v226, vcc
	v_cndmask_b32_e32 v137, 0, v231, vcc
	v_cndmask_b32_e32 v139, 0, v230, vcc
	v_cndmask_b32_e32 v124, 0, v229, vcc
	v_cndmask_b32_e32 v126, 0, v228, vcc
	v_cndmask_b32_e32 v132, 0, v227, vcc
	v_cndmask_b32_e32 v127, 0, v233, vcc
	v_cndmask_b32_e32 v133, 0, v232, vcc
	s_waitcnt vmcnt(4)
	v_cndmask_b32_e32 v138, 0, v234, vcc
	v_cndmask_b32_e32 v130, 0, v239, vcc
	v_cndmask_b32_e32 v134, 0, v238, vcc
	v_cndmask_b32_e32 v129, 0, v237, vcc
	v_cndmask_b32_e32 v131, 0, v236, vcc
	v_cndmask_b32_e32 v135, 0, v235, vcc
	v_cndmask_b32_e32 v125, 0, v241, vcc
	v_cndmask_b32_e32 v128, 0, v240, vcc
	s_waitcnt vmcnt(2)
	v_cndmask_b32_e32 v108, 0, v91, vcc
	v_cndmask_b32_e32 v110, 0, v90, vcc
	v_cndmask_b32_e32 v115, 0, v89, vcc
	v_cndmask_b32_e32 v120, 0, v88, vcc
	v_cndmask_b32_e32 v111, 0, v95, vcc
	v_cndmask_b32_e32 v116, 0, v94, vcc
	v_cndmask_b32_e32 v121, 0, v93, vcc
	v_cndmask_b32_e32 v123, 0, v92, vcc
	v_cmp_gt_u32_e32 vcc, s15, v87
	v_lshlrev_b32_e32 v208, 16, v52
	v_and_b32_e32 v52, 0xffff0000, v52
	s_waitcnt vmcnt(0)
	v_cndmask_b32_e32 v113, 0, v221, vcc
	v_cndmask_b32_e32 v117, 0, v220, vcc
	v_cndmask_b32_e32 v119, 0, v219, vcc
	v_cndmask_b32_e32 v122, 0, v218, vcc
	v_lshlrev_b32_e32 v86, 16, v97
	v_lshlrev_b32_e32 v87, 16, v161
	v_lshlrev_b32_e32 v88, 16, v98
	v_lshlrev_b32_e32 v89, 16, v169
	v_pk_mul_f32 v[100:101], v[86:87], v[88:89]
	v_and_b32_e32 v87, 0xffff0000, v161
	v_and_b32_e32 v86, 0xffff0000, v97
	v_and_b32_e32 v89, 0xffff0000, v169
	v_and_b32_e32 v88, 0xffff0000, v98
	v_pk_mul_f32 v[98:99], v[86:87], v[88:89]
	v_lshlrev_b32_e32 v86, 16, v96
	v_lshlrev_b32_e32 v87, 16, v159
	v_lshlrev_b32_e32 v88, 16, v149
	v_lshlrev_b32_e32 v89, 16, v167
	v_pk_mul_f32 v[94:95], v[86:87], v[88:89]
	v_and_b32_e32 v87, 0xffff0000, v159
	v_and_b32_e32 v86, 0xffff0000, v96
	v_and_b32_e32 v89, 0xffff0000, v167
	v_and_b32_e32 v88, 0xffff0000, v149
	v_pk_mul_f32 v[96:97], v[86:87], v[88:89]
	v_lshlrev_b32_e32 v86, 16, v143
	v_lshlrev_b32_e32 v87, 16, v157
	v_lshlrev_b32_e32 v88, 16, v147
	v_lshlrev_b32_e32 v89, 16, v165
	v_cndmask_b32_e32 v114, 0, v223, vcc
	v_cndmask_b32_e32 v118, 0, v222, vcc
	v_pk_mul_f32 v[90:91], v[86:87], v[88:89]
	v_and_b32_e32 v87, 0xffff0000, v157
	v_and_b32_e32 v86, 0xffff0000, v143
	v_and_b32_e32 v89, 0xffff0000, v165
	v_and_b32_e32 v88, 0xffff0000, v147
	v_cndmask_b32_e32 v109, 0, v225, vcc
	v_cndmask_b32_e32 v112, 0, v224, vcc
	v_pk_mul_f32 v[92:93], v[86:87], v[88:89]
	v_lshlrev_b32_e32 v86, 16, v141
	v_lshlrev_b32_e32 v87, 16, v155
	v_lshlrev_b32_e32 v88, 16, v145
	v_lshlrev_b32_e32 v89, 16, v163
	v_pk_mul_f32 v[86:87], v[86:87], v[88:89]
	v_and_b32_e32 v88, 0xffff0000, v141
	v_lshlrev_b32_e32 v143, 16, v190
	v_lshlrev_b32_e32 v141, 16, v194
	v_pk_mul_f32 v[172:173], v[60:61], v[100:101]
	v_pk_mul_f32 v[140:141], v[140:141], v[142:143]
	v_and_b32_e32 v147, 0xffff0000, v190
	v_fma_f32 v142, v8, v140, v172
	v_add_f32_e32 v142, v142, v173
	v_mul_f32_e32 v172, v142, v208
	v_pk_mul_f32 v[142:143], v[60:61], v[140:141]
	v_and_b32_e32 v145, 0xffff0000, v194
	v_fma_f32 v140, v8, v101, v142
	v_pk_mul_f32 v[174:175], v[4:5], v[98:99]
	v_add_f32_e32 v140, v140, v143
	v_pk_mul_f32 v[142:143], v[144:145], v[146:147]
	v_and_b32_e32 v89, 0xffff0000, v155
	v_fma_f32 v144, v9, v142, v174
	v_add_f32_e32 v144, v144, v175
	v_mul_f32_e32 v173, v144, v52
	v_pk_mul_f32 v[144:145], v[4:5], v[142:143]
	v_and_b32_e32 v155, 0xffff0000, v189
	v_lshlrev_b32_e32 v149, 16, v193
	v_fma_f32 v52, v9, v99, v144
	v_pk_mul_f32 v[176:177], v[66:67], v[94:95]
	v_pk_mul_f32 v[178:179], v[6:7], v[96:97]
	v_lshlrev_b32_e32 v159, 16, v188
	v_and_b32_e32 v163, 0xffff0000, v188
	v_lshlrev_b32_e32 v188, 16, v48
	v_and_b32_e32 v48, 0xffff0000, v48
	v_add_f32_e32 v52, v52, v145
	v_pk_mul_f32 v[144:145], v[148:149], v[150:151]
	v_pk_mul_f32 v[148:149], v[152:153], v[154:155]
	v_mul_f32_e32 v142, v52, v48
	v_and_b32_e32 v151, 0xffff0000, v53
	v_lshlrev_b32_e32 v150, 16, v53
	v_mov_b32_e32 v52, v144
	v_mov_b32_e32 v53, v148
	v_mov_b32_e32 v152, v176
	v_mov_b32_e32 v153, v178
	v_pk_fma_f32 v[52:53], v[10:11], v[52:53], v[152:153]
	v_mov_b32_e32 v178, v177
	v_pk_add_f32 v[52:53], v[52:53], v[178:179]
	v_mul_f32_e32 v174, v173, v173
	v_pk_mul_f32 v[52:53], v[52:53], v[150:151]
	v_fmac_f32_e32 v174, v172, v172
	v_pk_mul_f32 v[150:151], v[52:53], v[52:53]
	v_pk_mul_f32 v[146:147], v[66:67], v[144:145]
	v_add_f32_e32 v48, v150, v174
	v_add_f32_e32 v144, v151, v48
	v_pk_mul_f32 v[150:151], v[6:7], v[148:149]
	v_and_b32_e32 v153, 0xffff0000, v49
	v_lshlrev_b32_e32 v152, 16, v49
	v_mov_b32_e32 v48, v95
	v_mov_b32_e32 v49, v97
	v_mov_b32_e32 v154, v146
	v_mov_b32_e32 v155, v150
	v_pk_fma_f32 v[48:49], v[10:11], v[48:49], v[154:155]
	v_mov_b32_e32 v150, v147
	v_lshlrev_b32_e32 v157, 16, v192
	v_and_b32_e32 v161, 0xffff0000, v192
	v_pk_add_f32 v[48:49], v[48:49], v[150:151]
	v_pk_mul_f32 v[180:181], v[72:73], v[90:91]
	v_pk_mul_f32 v[182:183], v[16:17], v[92:93]
	v_pk_mul_f32 v[146:147], v[48:49], v[152:153]
	v_pk_mul_f32 v[150:151], v[156:157], v[158:159]
	v_pk_mul_f32 v[152:153], v[160:161], v[162:163]
	v_mov_b32_e32 v156, v150
	v_mov_b32_e32 v157, v152
	v_mov_b32_e32 v158, v180
	v_mov_b32_e32 v159, v182
	v_pk_fma_f32 v[156:157], v[20:21], v[156:157], v[158:159]
	v_mov_b32_e32 v182, v181
	v_and_b32_e32 v155, 0xffff0000, v54
	v_lshlrev_b32_e32 v154, 16, v54
	v_pk_add_f32 v[156:157], v[156:157], v[182:183]
	v_mul_f32_e32 v140, v140, v188
	v_mul_f32_e32 v175, v142, v142
	v_pk_mul_f32 v[154:155], v[156:157], v[154:155]
	v_fmac_f32_e32 v175, v140, v140
	v_pk_mul_f32 v[48:49], v[146:147], v[146:147]
	v_pk_mul_f32 v[156:157], v[154:155], v[154:155]
	v_add_f32_e32 v48, v48, v175
	v_add_f32_e32 v54, v156, v144
	v_add_f32_e32 v148, v49, v48
	v_pk_mul_f32 v[48:49], v[72:73], v[150:151]
	v_add_f32_e32 v144, v157, v54
	v_pk_mul_f32 v[156:157], v[16:17], v[152:153]
	v_mov_b32_e32 v160, v91
	v_mov_b32_e32 v161, v93
	v_mov_b32_e32 v162, v48
	v_mov_b32_e32 v163, v156
	v_pk_fma_f32 v[160:161], v[20:21], v[160:161], v[162:163]
	v_mov_b32_e32 v156, v49
	v_and_b32_e32 v159, 0xffff0000, v50
	v_lshlrev_b32_e32 v158, 16, v50
	v_pk_add_f32 v[48:49], v[160:161], v[156:157]
	v_pk_mul_f32 v[88:89], v[88:89], v[186:187]
	v_pk_mul_f32 v[156:157], v[48:49], v[158:159]
	v_lshlrev_b32_e32 v167, 16, v171
	v_pk_mul_f32 v[48:49], v[156:157], v[156:157]
	v_and_b32_e32 v171, 0xffff0000, v171
	v_lshlrev_b32_e32 v165, 16, v191
	v_and_b32_e32 v169, 0xffff0000, v191
	v_add_f32_e32 v48, v48, v148
	v_pk_mul_f32 v[184:185], v[78:79], v[86:87]
	v_pk_mul_f32 v[186:187], v[18:19], v[88:89]
	v_add_f32_e32 v148, v49, v48
	v_pk_mul_f32 v[158:159], v[164:165], v[166:167]
	v_pk_mul_f32 v[48:49], v[168:169], v[170:171]
	v_and_b32_e32 v163, 0xffff0000, v55
	v_lshlrev_b32_e32 v162, 16, v55
	v_mov_b32_e32 v54, v158
	v_mov_b32_e32 v55, v48
	v_mov_b32_e32 v164, v184
	v_mov_b32_e32 v165, v186
	v_pk_fma_f32 v[54:55], v[22:23], v[54:55], v[164:165]
	v_mov_b32_e32 v186, v185
	v_pk_add_f32 v[54:55], v[54:55], v[186:187]
	v_pk_mul_f32 v[160:161], v[78:79], v[158:159]
	v_pk_mul_f32 v[54:55], v[54:55], v[162:163]
	v_lshlrev_b32_e32 v164, 16, v200
	v_pk_mul_f32 v[162:163], v[54:55], v[54:55]
	v_lshlrev_b32_e32 v166, 16, v196
	v_add_f32_e32 v50, v162, v144
	v_add_f32_e32 v50, v163, v50
	v_and_b32_e32 v162, 0xffff0000, v197
	v_and_b32_e32 v163, 0xffff0000, v205
	v_lshlrev_b32_e32 v167, 16, v204
	v_lshlrev_b32_e32 v165, 16, v214
	s_waitcnt lgkmcnt(0)
	s_nop 1
	v_add_f32_dpp v50, v50, v50 quad_perm:[1,0,3,2] row_mask:0xf bank_mask:0xf
	v_and_b32_e32 v168, 0xffff0000, v200
	v_and_b32_e32 v170, 0xffff0000, v196
	v_and_b32_e32 v171, 0xffff0000, v204
	v_and_b32_e32 v169, 0xffff0000, v214
	s_waitcnt lgkmcnt(0)
	s_nop 1
	v_add_f32_dpp v50, v50, v50 quad_perm:[2,3,0,1] row_mask:0xf bank_mask:0xf
	v_lshlrev_b32_e32 v174, 16, v195
	v_lshlrev_b32_e32 v175, 16, v203
	v_and_b32_e32 v176, 0xffff0000, v199
	v_and_b32_e32 v178, 0xffff0000, v195
	s_waitcnt lgkmcnt(0)
	s_nop 1
	v_add_f32_dpp v50, v50, v50 row_half_mirror row_mask:0xf bank_mask:0xf
	v_and_b32_e32 v179, 0xffff0000, v203
	v_and_b32_e32 v177, 0xffff0000, v207
	s_waitcnt lgkmcnt(0)
	s_nop 1
	v_add_f32_dpp v50, v50, v50 row_mirror row_mask:0xf bank_mask:0xf
	s_nop 1
	v_mov_b32_e32 v144, v50
	s_nop 1
	v_permlane16_swap_b32_e32 v144, v50
	s_waitcnt lgkmcnt(0)
	v_add_f32_e32 v50, v50, v144
	v_fmamk_f32 v50, v50, 0x3b800000, v244
	v_cmp_gt_f32_e32 vcc, s7, v50
	v_mul_f32_e32 v144, 0x4b800000, v50
	s_nop 0
	v_cndmask_b32_e32 v50, v50, v144, vcc
	v_rsq_f32_e32 v50, v50
	s_nop 0
	v_mul_f32_e32 v144, 0x45800000, v50
	v_cndmask_b32_e32 v50, v50, v144, vcc
	v_mul_f32_e32 v53, v53, v50
	v_mul_f32_e32 v144, v172, v50
	v_mul_f32_e32 v150, v173, v50
	v_mul_f32_e32 v152, v52, v50
	v_cvt_pk_bf16_f32 v52, v144, v150
	v_cvt_pk_bf16_f32 v53, v152, v53
	v_mul_f32_e32 v154, v154, v50
	v_mul_f32_e32 v155, v155, v50
	v_mul_f32_e32 v158, v54, v50
	v_mul_f32_e32 v50, v55, v50
	v_cvt_pk_bf16_f32 v54, v154, v155
	v_cvt_pk_bf16_f32 v55, v158, v50
	global_store_dwordx4 v[84:85], v[52:55], off
	v_mov_b32_e32 v50, v87
	v_mov_b32_e32 v154, v160
	v_pk_mul_f32 v[52:53], v[18:19], v[48:49]
	v_and_b32_e32 v55, 0xffff0000, v51
	v_lshlrev_b32_e32 v54, 16, v51
	v_mov_b32_e32 v51, v89
	v_mov_b32_e32 v155, v52
	v_pk_fma_f32 v[50:51], v[22:23], v[50:51], v[154:155]
	v_mov_b32_e32 v52, v161
	v_pk_add_f32 v[50:51], v[50:51], v[52:53]
	v_lshlrev_b32_e32 v154, 16, v201
	v_pk_mul_f32 v[50:51], v[50:51], v[54:55]
	v_lshlrev_b32_e32 v155, 16, v215
	v_pk_mul_f32 v[52:53], v[50:51], v[50:51]
	v_and_b32_e32 v160, 0xffff0000, v201
	v_add_f32_e32 v48, v52, v148
	v_add_f32_e32 v48, v53, v48
	v_and_b32_e32 v161, 0xffff0000, v215
	v_mov_b32_e32 v148, v145
	v_mov_b32_e32 v152, v151
	v_lshlrev_b32_e32 v172, 16, v199
	s_waitcnt lgkmcnt(0)
	s_nop 1
	v_add_f32_dpp v48, v48, v48 quad_perm:[1,0,3,2] row_mask:0xf bank_mask:0xf
	v_lshlrev_b32_e32 v173, 16, v207
	s_waitcnt lgkmcnt(0)
	s_nop 1
	v_add_f32_dpp v48, v48, v48 quad_perm:[2,3,0,1] row_mask:0xf bank_mask:0xf
	s_waitcnt lgkmcnt(0)
	s_nop 1
	v_add_f32_dpp v48, v48, v48 row_half_mirror row_mask:0xf bank_mask:0xf
	s_waitcnt lgkmcnt(0)
	s_nop 1
	v_add_f32_dpp v48, v48, v48 row_mirror row_mask:0xf bank_mask:0xf
	s_nop 1
	v_mov_b32_e32 v52, v48
	s_nop 1
	v_permlane16_swap_b32_e32 v52, v48
	s_waitcnt lgkmcnt(0)
	v_add_f32_e32 v48, v48, v52
	v_fmamk_f32 v48, v48, 0x3b800000, v244
	v_cmp_gt_f32_e32 vcc, s7, v48
	v_mul_f32_e32 v52, 0x4b800000, v48
	s_nop 0
	v_cndmask_b32_e32 v48, v48, v52, vcc
	v_rsq_f32_e32 v48, v48
	s_nop 0
	v_mul_f32_e32 v52, 0x45800000, v48
	v_cndmask_b32_e32 v48, v48, v52, vcc
	v_mul_f32_e32 v52, v140, v48
	v_mul_f32_e32 v53, v142, v48
	v_mul_f32_e32 v54, v146, v48
	v_mul_f32_e32 v55, v147, v48
	v_mul_f32_e32 v140, v156, v48
	v_mul_f32_e32 v142, v157, v48
	v_mul_f32_e32 v144, v50, v48
	v_mul_f32_e32 v48, v51, v48
	v_cvt_pk_bf16_f32 v50, v52, v53
	v_cvt_pk_bf16_f32 v51, v54, v55
	v_cvt_pk_bf16_f32 v52, v140, v142
	v_cvt_pk_bf16_f32 v53, v144, v48
	global_store_dwordx4 v[84:85], v[50:53], off offset:2048
	v_lshlrev_b32_e32 v48, 16, v44
	v_and_b32_e32 v54, 0xffff0000, v202
	v_lshlrev_b32_e32 v50, 16, v202
	v_lshlrev_b32_e32 v52, 16, v198
	v_lshlrev_b32_e32 v53, 16, v206
	v_lshlrev_b32_e32 v51, 16, v216
	v_pk_mul_f32 v[180:181], v[50:51], v[52:53]
	v_and_b32_e32 v146, 0xffff0000, v198
	v_pk_mov_b32 v[50:51], v[100:101], v[180:181] op_sel:[1,0]
	v_and_b32_e32 v147, 0xffff0000, v206
	v_pk_mul_f32 v[50:51], v[60:61], v[50:51]
	v_and_b32_e32 v55, 0xffff0000, v216
	v_fma_f32 v50, v8, v141, v50
	v_add_f32_e32 v50, v50, v51
	v_mul_f32_e32 v144, v50, v48
	v_pk_mul_f32 v[50:51], v[62:63], v[180:181]
	v_pk_mul_f32 v[54:55], v[54:55], v[146:147]
	v_fma_f32 v48, v0, v141, v50
	v_add_f32_e32 v48, v48, v51
	v_pk_mov_b32 v[50:51], v[98:99], v[54:55] op_sel:[1,0]
	v_lshlrev_b32_e32 v140, 16, v40
	v_pk_mul_f32 v[50:51], v[4:5], v[50:51]
	v_mul_f32_e32 v150, v48, v140
	v_fma_f32 v48, v9, v143, v50
	v_lshlrev_b32_e32 v156, 16, v197
	v_and_b32_e32 v44, 0xffff0000, v44
	v_lshlrev_b32_e32 v157, 16, v205
	v_add_f32_e32 v48, v48, v51
	v_pk_mul_f32 v[50:51], v[64:65], v[54:55]
	v_mul_f32_e32 v146, v48, v44
	v_fma_f32 v44, v1, v143, v50
	v_pk_mul_f32 v[98:99], v[154:155], v[156:157]
	v_add_f32_e32 v44, v44, v51
	v_pk_mov_b32 v[50:51], v[94:95], v[98:99] op_sel:[1,0]
	v_pk_mul_f32 v[94:95], v[160:161], v[162:163]
	v_and_b32_e32 v40, 0xffff0000, v40
	v_pk_mov_b32 v[96:97], v[96:97], v[94:95] op_sel:[1,0]
	v_pk_mul_f32 v[50:51], v[66:67], v[50:51]
	v_pk_mul_f32 v[96:97], v[6:7], v[96:97]
	v_mul_f32_e32 v147, v44, v40
	v_and_b32_e32 v101, 0xffff0000, v45
	v_lshlrev_b32_e32 v100, 16, v45
	v_mov_b32_e32 v44, v50
	v_mov_b32_e32 v45, v96
	v_pk_fma_f32 v[44:45], v[10:11], v[148:149], v[44:45]
	v_mov_b32_e32 v96, v51
	v_pk_add_f32 v[44:45], v[44:45], v[96:97]
	v_mul_f32_e32 v48, v146, v146
	v_pk_mul_f32 v[44:45], v[44:45], v[100:101]
	v_fmac_f32_e32 v48, v144, v144
	v_pk_mul_f32 v[50:51], v[44:45], v[44:45]
	v_pk_mul_f32 v[52:53], v[68:69], v[98:99]
	v_add_f32_e32 v40, v50, v48
	v_add_f32_e32 v48, v51, v40
	v_pk_mul_f32 v[50:51], v[70:71], v[94:95]
	v_and_b32_e32 v97, 0xffff0000, v41
	v_lshlrev_b32_e32 v96, 16, v41
	v_mov_b32_e32 v40, v52
	v_mov_b32_e32 v41, v50
	v_pk_fma_f32 v[40:41], v[2:3], v[148:149], v[40:41]
	v_mov_b32_e32 v50, v53
	v_pk_add_f32 v[40:41], v[40:41], v[50:51]
	v_mul_f32_e32 v140, v147, v147
	v_pk_mul_f32 v[96:97], v[40:41], v[96:97]
	v_fmac_f32_e32 v140, v150, v150
	v_pk_mul_f32 v[40:41], v[96:97], v[96:97]
	v_pk_mul_f32 v[100:101], v[164:165], v[166:167]
	v_add_f32_e32 v40, v40, v140
	v_add_f32_e32 v142, v41, v40
	v_pk_mov_b32 v[40:41], v[90:91], v[100:101] op_sel:[1,0]
	v_pk_mul_f32 v[90:91], v[168:169], v[170:171]
	v_pk_mul_f32 v[40:41], v[72:73], v[40:41]
	v_pk_mov_b32 v[52:53], v[92:93], v[90:91] op_sel:[1,0]
	v_mov_b32_e32 v140, v40
	v_pk_mul_f32 v[52:53], v[16:17], v[52:53]
	v_and_b32_e32 v93, 0xffff0000, v46
	v_mov_b32_e32 v141, v52
	v_pk_fma_f32 v[140:141], v[20:21], v[152:153], v[140:141]
	v_mov_b32_e32 v52, v41
	v_lshlrev_b32_e32 v92, 16, v46
	v_pk_add_f32 v[40:41], v[140:141], v[52:53]
	v_pk_mul_f32 v[50:51], v[74:75], v[100:101]
	v_pk_mul_f32 v[52:53], v[40:41], v[92:93]
	v_mov_b32_e32 v140, v50
	v_pk_mul_f32 v[40:41], v[52:53], v[52:53]
	v_and_b32_e32 v93, 0xffff0000, v42
	v_add_f32_e32 v40, v40, v48
	v_add_f32_e32 v145, v41, v40
	v_pk_mul_f32 v[40:41], v[76:77], v[90:91]
	v_lshlrev_b32_e32 v92, 16, v42
	v_mov_b32_e32 v141, v40
	v_pk_fma_f32 v[140:141], v[12:13], v[152:153], v[140:141]
	v_mov_b32_e32 v40, v51
	v_pk_add_f32 v[40:41], v[140:141], v[40:41]
	v_pk_mul_f32 v[140:141], v[172:173], v[174:175]
	v_pk_mul_f32 v[92:93], v[40:41], v[92:93]
	v_and_b32_e32 v143, 0xffff0000, v47
	v_pk_mul_f32 v[40:41], v[92:93], v[92:93]
	v_mov_b32_e32 v48, v159
	v_add_f32_e32 v40, v40, v142
	v_add_f32_e32 v148, v41, v40
	v_pk_mov_b32 v[40:41], v[86:87], v[140:141] op_sel:[1,0]
	v_lshlrev_b32_e32 v142, 16, v47
	v_pk_mul_f32 v[50:51], v[78:79], v[40:41]
	v_pk_mul_f32 v[40:41], v[176:177], v[178:179]
	v_mov_b32_e32 v46, v50
	v_pk_mov_b32 v[88:89], v[88:89], v[40:41] op_sel:[1,0]
	v_pk_mul_f32 v[86:87], v[80:81], v[140:141]
	v_pk_mul_f32 v[88:89], v[18:19], v[88:89]
	v_and_b32_e32 v149, 0xffff0000, v129
	v_mov_b32_e32 v47, v88
	v_pk_fma_f32 v[46:47], v[22:23], v[48:49], v[46:47]
	v_mov_b32_e32 v88, v51
	v_pk_add_f32 v[46:47], v[46:47], v[88:89]
	s_nop 0
	v_pk_mul_f32 v[46:47], v[46:47], v[142:143]
	v_lshlrev_b32_e32 v143, 16, v125
	v_pk_mul_f32 v[50:51], v[46:47], v[46:47]
	v_lshlrev_b32_e32 v142, 16, v127
	v_add_f32_e32 v42, v50, v145
	v_add_f32_e32 v42, v51, v42
	v_lshlrev_b32_e32 v145, 16, v129
	s_waitcnt lgkmcnt(0)
	s_nop 1
	v_add_f32_dpp v42, v42, v42 quad_perm:[1,0,3,2] row_mask:0xf bank_mask:0xf
	s_waitcnt lgkmcnt(0)
	s_nop 1
	v_add_f32_dpp v42, v42, v42 quad_perm:[2,3,0,1] row_mask:0xf bank_mask:0xf
	s_waitcnt lgkmcnt(0)
	s_nop 1
	v_add_f32_dpp v42, v42, v42 row_half_mirror row_mask:0xf bank_mask:0xf
	s_waitcnt lgkmcnt(0)
	s_nop 1
	v_add_f32_dpp v42, v42, v42 row_mirror row_mask:0xf bank_mask:0xf
	s_nop 1
	v_mov_b32_e32 v50, v42
	s_nop 1
	v_permlane16_swap_b32_e32 v50, v42
	s_waitcnt lgkmcnt(0)
	v_add_f32_e32 v42, v42, v50
	v_fmamk_f32 v42, v42, 0x3b800000, v244
	v_cmp_gt_f32_e32 vcc, s7, v42
	v_mul_f32_e32 v50, 0x4b800000, v42
	s_nop 0
	v_cndmask_b32_e32 v42, v42, v50, vcc
	v_rsq_f32_e32 v42, v42
	s_nop 0
	v_mul_f32_e32 v50, 0x45800000, v42
	v_cndmask_b32_e32 v42, v42, v50, vcc
	v_add_co_u32_e32 v88, vcc, s34, v84
	v_mul_f32_e32 v50, v144, v42
	v_mul_f32_e32 v51, v146, v42
	v_mul_f32_e32 v44, v44, v42
	v_addc_co_u32_e32 v89, vcc, 0, v85, vcc
	v_mul_f32_e32 v45, v45, v42
	v_mul_f32_e32 v52, v52, v42
	v_mul_f32_e32 v53, v53, v42
	v_mul_f32_e32 v46, v46, v42
	v_cvt_pk_bf16_f32 v50, v50, v51
	v_cvt_pk_bf16_f32 v51, v44, v45
	v_add_co_u32_e32 v44, vcc, s15, v84
	v_mul_f32_e32 v42, v47, v42
	v_cvt_pk_bf16_f32 v52, v52, v53
	v_cvt_pk_bf16_f32 v53, v46, v42
	s_nop 0
	v_addc_co_u32_e32 v45, vcc, 0, v85, vcc
	v_pk_mul_f32 v[46:47], v[82:83], v[40:41]
	global_store_dwordx4 v[44:45], v[50:53], off offset:-4096
	v_mov_b32_e32 v42, v86
	v_lshlrev_b32_e32 v144, 16, v124
	v_and_b32_e32 v51, 0xffff0000, v43
	v_lshlrev_b32_e32 v50, 16, v43
	v_mov_b32_e32 v43, v46
	v_pk_fma_f32 v[42:43], v[14:15], v[48:49], v[42:43]
	v_mov_b32_e32 v46, v87
	v_pk_add_f32 v[42:43], v[42:43], v[46:47]
	v_lshlrev_b32_e32 v86, 16, v132
	v_pk_mul_f32 v[42:43], v[42:43], v[50:51]
	v_lshlrev_b32_e32 v87, 16, v135
	v_pk_mul_f32 v[46:47], v[42:43], v[42:43]
	v_lshlrev_b32_e32 v53, 16, v130
	v_add_f32_e32 v46, v46, v148
	v_add_f32_e32 v46, v47, v46
	v_and_b32_e32 v148, 0xffff0000, v124
	v_lshlrev_b32_e32 v124, 16, v36
	v_and_b32_e32 v36, 0xffff0000, v36
	v_and_b32_e32 v146, 0xffff0000, v127
	s_waitcnt lgkmcnt(0)
	s_nop 1
	v_add_f32_dpp v46, v46, v46 quad_perm:[1,0,3,2] row_mask:0xf bank_mask:0xf
	v_and_b32_e32 v127, 0xffff0000, v131
	s_waitcnt lgkmcnt(0)
	s_nop 1
	v_add_f32_dpp v46, v46, v46 quad_perm:[2,3,0,1] row_mask:0xf bank_mask:0xf
	s_waitcnt lgkmcnt(0)
	s_nop 1
	v_add_f32_dpp v46, v46, v46 row_half_mirror row_mask:0xf bank_mask:0xf
	s_waitcnt lgkmcnt(0)
	s_nop 1
	v_add_f32_dpp v46, v46, v46 row_mirror row_mask:0xf bank_mask:0xf
	s_nop 1
	v_mov_b32_e32 v47, v46
	s_nop 1
	v_permlane16_swap_b32_e32 v47, v46
	s_waitcnt lgkmcnt(0)
	v_add_f32_e32 v46, v46, v47
	v_fmamk_f32 v46, v46, 0x3b800000, v244
	v_cmp_gt_f32_e32 vcc, s7, v46
	v_mul_f32_e32 v47, 0x4b800000, v46
	s_nop 0
	v_cndmask_b32_e32 v46, v46, v47, vcc
	v_rsq_f32_e32 v46, v46
	s_nop 0
	v_mul_f32_e32 v47, 0x45800000, v46
	v_cndmask_b32_e32 v46, v46, v47, vcc
	v_mul_f32_e32 v47, v150, v46
	v_mul_f32_e32 v48, v147, v46
	v_mul_f32_e32 v49, v96, v46
	v_mul_f32_e32 v50, v97, v46
	v_mul_f32_e32 v51, v92, v46
	v_mul_f32_e32 v52, v93, v46
	v_mul_f32_e32 v42, v42, v46
	v_mul_f32_e32 v43, v43, v46
	v_cvt_pk_bf16_f32 v46, v47, v48
	v_cvt_pk_bf16_f32 v47, v49, v50
	v_cvt_pk_bf16_f32 v48, v51, v52
	v_cvt_pk_bf16_f32 v49, v42, v43
	global_store_dwordx4 v[88:89], v[46:49], off offset:2048
	v_lshlrev_b32_e32 v42, 16, v139
	v_lshlrev_b32_e32 v43, 16, v134
	v_lshlrev_b32_e32 v46, 16, v136
	v_lshlrev_b32_e32 v47, 16, v138
	v_pk_mul_f32 v[42:43], v[42:43], v[46:47]
	v_mov_b32_e32 v46, v180
	v_mov_b32_e32 v47, v42
	v_pk_mul_f32 v[46:47], v[60:61], v[46:47]
	v_and_b32_e32 v48, 0xffff0000, v139
	v_fma_f32 v46, v8, v181, v46
	v_add_f32_e32 v46, v46, v47
	v_mul_f32_e32 v124, v46, v124
	v_pk_mul_f32 v[46:47], v[62:63], v[42:43]
	v_and_b32_e32 v50, 0xffff0000, v136
	v_fma_f32 v46, v0, v181, v46
	v_and_b32_e32 v51, 0xffff0000, v138
	v_and_b32_e32 v49, 0xffff0000, v134
	v_and_b32_e32 v147, 0xffff0000, v125
	v_lshlrev_b32_e32 v125, 16, v32
	v_add_f32_e32 v46, v46, v47
	v_mul_f32_e32 v125, v46, v125
	v_pk_mul_f32 v[46:47], v[48:49], v[50:51]
	v_mov_b32_e32 v48, v54
	v_mov_b32_e32 v49, v46
	v_pk_mul_f32 v[48:49], v[4:5], v[48:49]
	v_lshlrev_b32_e32 v52, 16, v137
	v_fma_f32 v48, v9, v55, v48
	v_add_f32_e32 v48, v48, v49
	v_and_b32_e32 v88, 0xffff0000, v137
	v_lshlrev_b32_e32 v97, 16, v128
	v_and_b32_e32 v137, 0xffff0000, v128
	v_mul_f32_e32 v128, v48, v36
	v_pk_mul_f32 v[48:49], v[64:65], v[46:47]
	v_and_b32_e32 v92, 0xffff0000, v132
	v_and_b32_e32 v93, 0xffff0000, v135
	v_and_b32_e32 v89, 0xffff0000, v130
	v_fma_f32 v36, v1, v55, v48
	v_add_f32_e32 v36, v36, v49
	v_pk_mul_f32 v[48:49], v[52:53], v[86:87]
	v_pk_mul_f32 v[54:55], v[88:89], v[92:93]
	v_mov_b32_e32 v50, v98
	v_mov_b32_e32 v51, v48
	v_mov_b32_e32 v86, v94
	v_mov_b32_e32 v87, v54
	v_and_b32_e32 v32, 0xffff0000, v32
	v_pk_mul_f32 v[50:51], v[66:67], v[50:51]
	v_pk_mul_f32 v[86:87], v[6:7], v[86:87]
	v_mul_f32_e32 v130, v36, v32
	v_and_b32_e32 v89, 0xffff0000, v37
	v_lshlrev_b32_e32 v88, 16, v37
	v_mov_b32_e32 v94, v99
	v_mov_b32_e32 v36, v50
	v_mov_b32_e32 v37, v86
	v_pk_fma_f32 v[36:37], v[10:11], v[94:95], v[36:37]
	v_mov_b32_e32 v86, v51
	v_pk_add_f32 v[36:37], v[36:37], v[86:87]
	v_mul_f32_e32 v129, v128, v128
	v_pk_mul_f32 v[36:37], v[36:37], v[88:89]
	v_fmac_f32_e32 v129, v124, v124
	v_pk_mul_f32 v[50:51], v[36:37], v[36:37]
	v_pk_mul_f32 v[52:53], v[68:69], v[48:49]
	v_add_f32_e32 v32, v50, v129
	v_add_f32_e32 v98, v51, v32
	v_pk_mul_f32 v[50:51], v[70:71], v[54:55]
	v_and_b32_e32 v87, 0xffff0000, v33
	v_lshlrev_b32_e32 v86, 16, v33
	v_mov_b32_e32 v32, v52
	v_mov_b32_e32 v33, v50
	v_pk_fma_f32 v[32:33], v[2:3], v[94:95], v[32:33]
	v_mov_b32_e32 v50, v53
	v_pk_add_f32 v[32:33], v[32:33], v[50:51]
	v_lshlrev_b32_e32 v96, 16, v133
	v_and_b32_e32 v136, 0xffff0000, v133
	v_lshlrev_b32_e32 v133, 16, v131
	v_mul_f32_e32 v131, v130, v130
	v_pk_mul_f32 v[50:51], v[32:33], v[86:87]
	v_lshlrev_b32_e32 v132, 16, v126
	v_and_b32_e32 v126, 0xffff0000, v126
	v_fmac_f32_e32 v131, v125, v125
	v_pk_mul_f32 v[32:33], v[50:51], v[50:51]
	v_pk_mul_f32 v[52:53], v[96:97], v[132:133]
	v_add_f32_e32 v32, v32, v131
	v_pk_mul_f32 v[88:89], v[136:137], v[126:127]
	v_add_f32_e32 v99, v33, v32
	v_mov_b32_e32 v32, v100
	v_mov_b32_e32 v33, v52
	v_mov_b32_e32 v92, v90
	v_mov_b32_e32 v93, v88
	v_pk_mul_f32 v[32:33], v[72:73], v[32:33]
	v_pk_mul_f32 v[92:93], v[16:17], v[92:93]
	v_mov_b32_e32 v90, v101
	v_mov_b32_e32 v96, v32
	v_mov_b32_e32 v97, v92
	v_pk_fma_f32 v[96:97], v[20:21], v[90:91], v[96:97]
	v_mov_b32_e32 v92, v33
	v_and_b32_e32 v95, 0xffff0000, v38
	v_lshlrev_b32_e32 v94, 16, v38
	v_pk_add_f32 v[32:33], v[96:97], v[92:93]
	v_pk_mul_f32 v[86:87], v[74:75], v[52:53]
	v_pk_mul_f32 v[92:93], v[32:33], v[94:95]
	v_mov_b32_e32 v96, v86
	v_pk_mul_f32 v[32:33], v[92:93], v[92:93]
	v_and_b32_e32 v95, 0xffff0000, v34
	v_add_f32_e32 v32, v32, v98
	v_add_f32_e32 v126, v33, v32
	v_pk_mul_f32 v[32:33], v[76:77], v[88:89]
	v_lshlrev_b32_e32 v94, 16, v34
	v_mov_b32_e32 v97, v32
	v_pk_fma_f32 v[90:91], v[12:13], v[90:91], v[96:97]
	v_mov_b32_e32 v32, v87
	v_pk_add_f32 v[32:33], v[90:91], v[32:33]
	v_pk_mul_f32 v[90:91], v[142:143], v[144:145]
	v_pk_mul_f32 v[86:87], v[32:33], v[94:95]
	v_mov_b32_e32 v98, v40
	v_pk_mul_f32 v[32:33], v[86:87], v[86:87]
	v_and_b32_e32 v101, 0xffff0000, v39
	v_add_f32_e32 v32, v32, v99
	v_add_f32_e32 v127, v33, v32
	v_mov_b32_e32 v32, v140
	v_mov_b32_e32 v33, v90
	v_pk_mul_f32 v[94:95], v[78:79], v[32:33]
	v_pk_mul_f32 v[32:33], v[146:147], v[148:149]
	v_lshlrev_b32_e32 v100, 16, v39
	v_mov_b32_e32 v99, v32
	v_pk_mul_f32 v[98:99], v[18:19], v[98:99]
	v_mov_b32_e32 v40, v141
	v_mov_b32_e32 v38, v94
	v_mov_b32_e32 v39, v98
	v_pk_fma_f32 v[38:39], v[22:23], v[40:41], v[38:39]
	v_mov_b32_e32 v98, v95
	v_pk_add_f32 v[38:39], v[38:39], v[98:99]
	v_pk_mul_f32 v[96:97], v[80:81], v[90:91]
	v_pk_mul_f32 v[38:39], v[38:39], v[100:101]
	v_and_b32_e32 v100, 0xffff0000, v110
	v_pk_mul_f32 v[94:95], v[38:39], v[38:39]
	v_and_b32_e32 v101, 0xffff0000, v117
	v_add_f32_e32 v34, v94, v126
	v_add_f32_e32 v34, v95, v34
	s_waitcnt lgkmcnt(0)
	s_nop 1
	v_add_f32_dpp v34, v34, v34 quad_perm:[1,0,3,2] row_mask:0xf bank_mask:0xf
	s_waitcnt lgkmcnt(0)
	s_nop 1
	v_add_f32_dpp v34, v34, v34 quad_perm:[2,3,0,1] row_mask:0xf bank_mask:0xf
	s_waitcnt lgkmcnt(0)
	s_nop 1
	v_add_f32_dpp v34, v34, v34 row_half_mirror row_mask:0xf bank_mask:0xf
	s_waitcnt lgkmcnt(0)
	s_nop 1
	v_add_f32_dpp v34, v34, v34 row_mirror row_mask:0xf bank_mask:0xf
	s_nop 1
	v_mov_b32_e32 v94, v34
	s_nop 1
	v_permlane16_swap_b32_e32 v94, v34
	s_waitcnt lgkmcnt(0)
	v_add_f32_e32 v34, v34, v94
	v_fmamk_f32 v34, v34, 0x3b800000, v244
	v_cmp_gt_f32_e32 vcc, s7, v34
	v_mul_f32_e32 v94, 0x4b800000, v34
	s_nop 0
	v_cndmask_b32_e32 v34, v34, v94, vcc
	v_rsq_f32_e32 v34, v34
	s_nop 0
	v_mul_f32_e32 v94, 0x45800000, v34
	v_cndmask_b32_e32 v34, v34, v94, vcc
	v_mul_f32_e32 v37, v37, v34
	v_mul_f32_e32 v94, v124, v34
	v_mul_f32_e32 v95, v128, v34
	v_mul_f32_e32 v98, v36, v34
	v_cvt_pk_bf16_f32 v36, v94, v95
	v_cvt_pk_bf16_f32 v37, v98, v37
	v_mul_f32_e32 v92, v92, v34
	v_mul_f32_e32 v93, v93, v34
	v_mul_f32_e32 v99, v38, v34
	v_mul_f32_e32 v34, v39, v34
	v_cvt_pk_bf16_f32 v38, v92, v93
	v_cvt_pk_bf16_f32 v39, v99, v34
	global_store_dwordx4 v[44:45], v[36:39], off
	v_mov_b32_e32 v34, v96
	v_lshlrev_b32_e32 v96, 16, v110
	v_pk_mul_f32 v[36:37], v[82:83], v[32:33]
	v_and_b32_e32 v39, 0xffff0000, v35
	v_lshlrev_b32_e32 v38, 16, v35
	v_mov_b32_e32 v35, v36
	v_pk_fma_f32 v[34:35], v[14:15], v[40:41], v[34:35]
	v_mov_b32_e32 v36, v97
	v_pk_add_f32 v[34:35], v[34:35], v[36:37]
	v_lshlrev_b32_e32 v110, 16, v111
	v_pk_mul_f32 v[34:35], v[34:35], v[38:39]
	v_lshlrev_b32_e32 v94, 16, v116
	v_pk_mul_f32 v[36:37], v[34:35], v[34:35]
	v_and_b32_e32 v98, 0xffff0000, v116
	v_add_f32_e32 v36, v36, v127
	v_add_f32_e32 v36, v37, v36
	v_lshlrev_b32_e32 v116, 16, v108
	v_and_b32_e32 v124, 0xffff0000, v108
	v_lshlrev_b32_e32 v108, 16, v28
	v_and_b32_e32 v28, 0xffff0000, v28
	s_waitcnt lgkmcnt(0)
	s_nop 1
	v_add_f32_dpp v36, v36, v36 quad_perm:[1,0,3,2] row_mask:0xf bank_mask:0xf
	v_and_b32_e32 v92, 0xffff0000, v115
	v_and_b32_e32 v93, 0xffff0000, v119
	v_lshlrev_b32_e32 v95, 16, v112
	v_and_b32_e32 v99, 0xffff0000, v112
	s_waitcnt lgkmcnt(0)
	s_nop 1
	v_add_f32_dpp v36, v36, v36 quad_perm:[2,3,0,1] row_mask:0xf bank_mask:0xf
	v_lshlrev_b32_e32 v97, 16, v117
	v_lshlrev_b32_e32 v117, 16, v113
	s_waitcnt lgkmcnt(0)
	s_nop 1
	v_add_f32_dpp v36, v36, v36 row_half_mirror row_mask:0xf bank_mask:0xf
	s_waitcnt lgkmcnt(0)
	s_nop 1
	v_add_f32_dpp v36, v36, v36 row_mirror row_mask:0xf bank_mask:0xf
	s_nop 1
	v_mov_b32_e32 v37, v36
	s_nop 1
	v_permlane16_swap_b32_e32 v37, v36
	s_waitcnt lgkmcnt(0)
	v_add_f32_e32 v36, v36, v37
	v_fmamk_f32 v36, v36, 0x3b800000, v244
	v_cmp_gt_f32_e32 vcc, s7, v36
	v_mul_f32_e32 v37, 0x4b800000, v36
	s_nop 0
	v_cndmask_b32_e32 v36, v36, v37, vcc
	v_rsq_f32_e32 v36, v36
	s_nop 0
	v_mul_f32_e32 v37, 0x45800000, v36
	v_cndmask_b32_e32 v36, v36, v37, vcc
	v_mul_f32_e32 v37, v125, v36
	v_mul_f32_e32 v38, v130, v36
	v_mul_f32_e32 v39, v50, v36
	v_mul_f32_e32 v40, v51, v36
	v_mul_f32_e32 v41, v86, v36
	v_mul_f32_e32 v50, v87, v36
	v_mul_f32_e32 v51, v34, v36
	v_mul_f32_e32 v86, v35, v36
	v_cvt_pk_bf16_f32 v34, v37, v38
	v_cvt_pk_bf16_f32 v35, v39, v40
	v_cvt_pk_bf16_f32 v36, v41, v50
	v_cvt_pk_bf16_f32 v37, v51, v86
	global_store_dwordx4 v[44:45], v[34:37], off offset:2048
	v_and_b32_e32 v38, 0xffff0000, v123
	v_and_b32_e32 v40, 0xffff0000, v120
	v_lshlrev_b32_e32 v34, 16, v123
	v_lshlrev_b32_e32 v36, 16, v120
	v_lshlrev_b32_e32 v37, 16, v122
	v_lshlrev_b32_e32 v35, 16, v118
	v_pk_mul_f32 v[34:35], v[34:35], v[36:37]
	v_mov_b32_e32 v36, v42
	v_mov_b32_e32 v37, v34
	v_pk_mul_f32 v[34:35], v[62:63], v[34:35]
	v_pk_mul_f32 v[36:37], v[60:61], v[36:37]
	v_fma_f32 v34, v0, v43, v34
	v_lshlrev_b32_e32 v44, 16, v121
	v_and_b32_e32 v86, 0xffff0000, v121
	v_and_b32_e32 v120, 0xffff0000, v111
	v_and_b32_e32 v41, 0xffff0000, v122
	v_and_b32_e32 v39, 0xffff0000, v118
	v_lshlrev_b32_e32 v111, 16, v109
	v_and_b32_e32 v121, 0xffff0000, v109
	v_lshlrev_b32_e32 v109, 16, v24
	v_fma_f32 v36, v8, v43, v36
	v_add_f32_e32 v34, v34, v35
	v_add_f32_e32 v36, v36, v37
	v_mul_f32_e32 v109, v34, v109
	v_pk_mul_f32 v[34:35], v[38:39], v[40:41]
	v_mul_f32_e32 v108, v36, v108
	v_mov_b32_e32 v36, v46
	v_mov_b32_e32 v37, v34
	v_pk_mul_f32 v[36:37], v[4:5], v[36:37]
	v_pk_mul_f32 v[34:35], v[64:65], v[34:35]
	v_fma_f32 v36, v9, v47, v36
	v_add_f32_e32 v36, v36, v37
	v_lshlrev_b32_e32 v50, 16, v115
	v_lshlrev_b32_e32 v51, 16, v119
	v_lshlrev_b32_e32 v45, 16, v114
	v_and_b32_e32 v87, 0xffff0000, v114
	v_mul_f32_e32 v112, v36, v28
	v_fma_f32 v28, v1, v47, v34
	v_add_f32_e32 v28, v28, v35
	v_pk_mul_f32 v[34:35], v[44:45], v[50:51]
	v_pk_mul_f32 v[38:39], v[86:87], v[92:93]
	v_mov_b32_e32 v36, v48
	v_mov_b32_e32 v37, v34
	v_mov_b32_e32 v40, v54
	v_mov_b32_e32 v41, v38
	v_and_b32_e32 v24, 0xffff0000, v24
	v_pk_mul_f32 v[36:37], v[66:67], v[36:37]
	v_pk_mul_f32 v[40:41], v[6:7], v[40:41]
	v_and_b32_e32 v125, 0xffff0000, v113
	v_mul_f32_e32 v113, v28, v24
	v_and_b32_e32 v43, 0xffff0000, v29
	v_lshlrev_b32_e32 v42, 16, v29
	v_mov_b32_e32 v54, v49
	v_mov_b32_e32 v28, v36
	v_mov_b32_e32 v29, v40
	v_pk_fma_f32 v[28:29], v[10:11], v[54:55], v[28:29]
	v_mov_b32_e32 v40, v37
	v_pk_add_f32 v[28:29], v[28:29], v[40:41]
	v_mul_f32_e32 v46, v112, v112
	v_pk_mul_f32 v[28:29], v[28:29], v[42:43]
	v_fmac_f32_e32 v46, v108, v108
	v_pk_mul_f32 v[36:37], v[28:29], v[28:29]
	v_pk_mul_f32 v[34:35], v[68:69], v[34:35]
	v_add_f32_e32 v24, v36, v46
	v_add_f32_e32 v46, v37, v24
	v_pk_mul_f32 v[36:37], v[70:71], v[38:39]
	v_and_b32_e32 v39, 0xffff0000, v25
	v_lshlrev_b32_e32 v38, 16, v25
	v_mov_b32_e32 v24, v34
	v_mov_b32_e32 v25, v36
	v_pk_fma_f32 v[24:25], v[2:3], v[54:55], v[24:25]
	v_mov_b32_e32 v36, v35
	v_pk_add_f32 v[24:25], v[24:25], v[36:37]
	v_mul_f32_e32 v47, v113, v113
	v_pk_mul_f32 v[24:25], v[24:25], v[38:39]
	v_fmac_f32_e32 v47, v109, v109
	v_pk_mul_f32 v[34:35], v[24:25], v[24:25]
	v_pk_mul_f32 v[38:39], v[98:99], v[100:101]
	v_add_f32_e32 v34, v34, v47
	v_add_f32_e32 v47, v35, v34
	v_pk_mul_f32 v[34:35], v[94:95], v[96:97]
	v_mov_b32_e32 v36, v52
	v_mov_b32_e32 v37, v34
	v_mov_b32_e32 v40, v88
	v_mov_b32_e32 v41, v38
	v_pk_mul_f32 v[36:37], v[72:73], v[36:37]
	v_pk_mul_f32 v[40:41], v[16:17], v[40:41]
	v_mov_b32_e32 v88, v53
	v_mov_b32_e32 v44, v36
	v_mov_b32_e32 v45, v40
	v_pk_fma_f32 v[44:45], v[20:21], v[88:89], v[44:45]
	v_mov_b32_e32 v40, v37
	v_and_b32_e32 v43, 0xffff0000, v30
	v_lshlrev_b32_e32 v42, 16, v30
	v_pk_add_f32 v[36:37], v[44:45], v[40:41]
	v_pk_mul_f32 v[34:35], v[74:75], v[34:35]
	v_pk_mul_f32 v[36:37], v[36:37], v[42:43]
	v_pk_mul_f32 v[38:39], v[76:77], v[38:39]
	v_pk_mul_f32 v[40:41], v[36:37], v[36:37]
	v_mov_b32_e32 v42, v34
	v_mov_b32_e32 v43, v38
	v_add_f32_e32 v30, v40, v46
	v_pk_fma_f32 v[42:43], v[12:13], v[88:89], v[42:43]
	v_mov_b32_e32 v38, v35
	v_add_f32_e32 v48, v41, v30
	v_and_b32_e32 v41, 0xffff0000, v26
	v_lshlrev_b32_e32 v40, 16, v26
	v_pk_add_f32 v[34:35], v[42:43], v[38:39]
	v_pk_mul_f32 v[42:43], v[120:121], v[124:125]
	v_pk_mul_f32 v[34:35], v[34:35], v[40:41]
	v_mov_b32_e32 v40, v90
	v_pk_mul_f32 v[38:39], v[34:35], v[34:35]
	v_mov_b32_e32 v44, v32
	v_add_f32_e32 v26, v38, v47
	v_add_f32_e32 v49, v39, v26
	v_pk_mul_f32 v[38:39], v[110:111], v[116:117]
	v_mov_b32_e32 v45, v42
	v_mov_b32_e32 v41, v38
	v_pk_mul_f32 v[40:41], v[78:79], v[40:41]
	v_pk_mul_f32 v[44:45], v[18:19], v[44:45]
	v_and_b32_e32 v47, 0xffff0000, v31
	v_lshlrev_b32_e32 v46, 16, v31
	v_mov_b32_e32 v32, v91
	v_mov_b32_e32 v30, v40
	v_mov_b32_e32 v31, v44
	v_pk_fma_f32 v[30:31], v[22:23], v[32:33], v[30:31]
	v_mov_b32_e32 v44, v41
	v_pk_add_f32 v[30:31], v[30:31], v[44:45]
	v_pk_mul_f32 v[38:39], v[80:81], v[38:39]
	v_pk_mul_f32 v[30:31], v[30:31], v[46:47]
	s_nop 0
	v_pk_mul_f32 v[40:41], v[30:31], v[30:31]
	s_nop 0
	v_add_f32_e32 v26, v40, v48
	v_add_f32_e32 v26, v41, v26
	s_waitcnt lgkmcnt(0)
	s_nop 1
	v_add_f32_dpp v26, v26, v26 quad_perm:[1,0,3,2] row_mask:0xf bank_mask:0xf
	s_waitcnt lgkmcnt(0)
	s_nop 1
	v_add_f32_dpp v26, v26, v26 quad_perm:[2,3,0,1] row_mask:0xf bank_mask:0xf
	s_waitcnt lgkmcnt(0)
	s_nop 1
	v_add_f32_dpp v26, v26, v26 row_half_mirror row_mask:0xf bank_mask:0xf
	s_waitcnt lgkmcnt(0)
	s_nop 1
	v_add_f32_dpp v26, v26, v26 row_mirror row_mask:0xf bank_mask:0xf
	s_nop 1
	v_mov_b32_e32 v40, v26
	s_nop 1
	v_permlane16_swap_b32_e32 v40, v26
	s_waitcnt lgkmcnt(0)
	v_add_f32_e32 v26, v26, v40
	v_fmamk_f32 v26, v26, 0x3b800000, v244
	v_cmp_gt_f32_e32 vcc, s7, v26
	v_mul_f32_e32 v40, 0x4b800000, v26
	s_nop 0
	v_cndmask_b32_e32 v26, v26, v40, vcc
	v_rsq_f32_e32 v26, v26
	s_nop 0
	v_mul_f32_e32 v40, 0x45800000, v26
	v_cndmask_b32_e32 v26, v26, v40, vcc
	v_mul_f32_e32 v29, v29, v26
	v_mul_f32_e32 v36, v36, v26
	v_mul_f32_e32 v40, v108, v26
	v_mul_f32_e32 v41, v112, v26
	v_mul_f32_e32 v44, v28, v26
	v_mul_f32_e32 v37, v37, v26
	v_mul_f32_e32 v45, v30, v26
	v_cvt_pk_bf16_f32 v28, v40, v41
	v_cvt_pk_bf16_f32 v29, v44, v29
	v_cvt_pk_bf16_f32 v30, v36, v37
	v_add_co_u32_e32 v36, vcc, s35, v84
	v_mul_f32_e32 v26, v31, v26
	s_nop 0
	v_addc_co_u32_e32 v37, vcc, 0, v85, vcc
	v_cvt_pk_bf16_f32 v31, v45, v26
	global_store_dwordx4 v[36:37], v[28:31], off
	v_mov_b32_e32 v26, v38
	s_nop 0
	v_pk_mul_f32 v[28:29], v[82:83], v[42:43]
	v_and_b32_e32 v31, 0xffff0000, v27
	v_lshlrev_b32_e32 v30, 16, v27
	v_mov_b32_e32 v27, v28
	v_pk_fma_f32 v[26:27], v[14:15], v[32:33], v[26:27]
	v_mov_b32_e32 v28, v39
	v_pk_add_f32 v[26:27], v[26:27], v[28:29]
	s_nop 0
	v_pk_mul_f32 v[26:27], v[26:27], v[30:31]
	s_nop 0
	v_pk_mul_f32 v[28:29], v[26:27], v[26:27]
	s_nop 0
	v_add_f32_e32 v28, v28, v49
	v_add_f32_e32 v28, v29, v28
	s_waitcnt lgkmcnt(0)
	s_nop 1
	v_add_f32_dpp v28, v28, v28 quad_perm:[1,0,3,2] row_mask:0xf bank_mask:0xf
	s_waitcnt lgkmcnt(0)
	s_nop 1
	v_add_f32_dpp v28, v28, v28 quad_perm:[2,3,0,1] row_mask:0xf bank_mask:0xf
	s_waitcnt lgkmcnt(0)
	s_nop 1
	v_add_f32_dpp v28, v28, v28 row_half_mirror row_mask:0xf bank_mask:0xf
	s_waitcnt lgkmcnt(0)
	s_nop 1
	v_add_f32_dpp v28, v28, v28 row_mirror row_mask:0xf bank_mask:0xf
	s_nop 1
	v_mov_b32_e32 v29, v28
	s_nop 1
	v_permlane16_swap_b32_e32 v29, v28
	s_waitcnt lgkmcnt(0)
	v_add_f32_e32 v28, v28, v29
	v_fmamk_f32 v28, v28, 0x3b800000, v244
	v_cmp_gt_f32_e32 vcc, s7, v28
	v_mul_f32_e32 v29, 0x4b800000, v28
	s_nop 0
	v_cndmask_b32_e32 v28, v28, v29, vcc
	v_rsq_f32_e32 v28, v28
	s_nop 0
	v_mul_f32_e32 v29, 0x45800000, v28
	v_cndmask_b32_e32 v28, v28, v29, vcc
	v_mul_f32_e32 v25, v25, v28
	v_mul_f32_e32 v27, v27, v28
	v_mul_f32_e32 v29, v109, v28
	v_mul_f32_e32 v30, v113, v28
	v_mul_f32_e32 v31, v24, v28
	v_mul_f32_e32 v32, v34, v28
	v_mul_f32_e32 v33, v35, v28
	v_mul_f32_e32 v34, v26, v28
	v_cvt_pk_bf16_f32 v24, v29, v30
	v_cvt_pk_bf16_f32 v25, v31, v25
	v_cvt_pk_bf16_f32 v26, v32, v33
	v_cvt_pk_bf16_f32 v27, v34, v27
	global_store_dwordx4 v[36:37], v[24:27], off offset:2048
	s_cbranch_scc1 .LBB0_227
